# diff_attn main loop staggered: waves 4-7 run PV of step t-1 before a mid-step barrier, waves 0-3 hit the mid barrier right after the S MFMAs; next-tile LDS writes after the mid barrier for both (stack
# baseline (speedup 1.0000x reference)
; #define LAS __attribute__((address_space(3)))
; #define MFMA32(a, b, c) __builtin_amdgcn_mfma_f32_32x32x16_bf16((a), (b), (c), 0, 0, 0)
; DI f32x16 zero16() { f32x16 z; for (int i = 0; i < 16; ++i) z[i] = 0.f; return z; }
; DI void diff_attn_phase(int wv, LAS unsigned char* lds, const bf16_t* qk, const bf16_t* vt, bf16_t* ob, const float* lq1, const float* lk1, const float* lq2, const float* lk2,
;                         const float* subg, int layer_idx) {
;     ...
;         for (int t = 0; t < tmain; ++t) {
;             const int key0 = t * 64;
;             const bool more = true;
;             if (more) {
; #pragma unroll
;                 for (int i = 0; i < 2; ++i) gk[i] = *(const u32x4*)(kg + (size_t)(key0 + 64 + i * 32) * 2048); }
;             LAS unsigned char* buf = lds + (t & 1) * DA_BUF;
;             {
;                 f32x16 S0 = zero16(), S1 = zero16();
;                 {
;                     bf16x8 kf[2][4];
; #pragma unroll
;                     for (int sub = 0; sub < 2; ++sub)
; #pragma unroll
;                         for (int ks = 0; ks < 4; ++ks) kf[sub][ks] = *(const LAS bf16x8*)(buf + koff + sub * 32 * DA_KP + ks * 32);
; #pragma unroll
;                     for (int ks = 0; ks < 4; ++ks) { const bf16x8 qfr = *(const LAS bf16x8*)(qlds + ks * 1024); S0 = MFMA32(kf[0][ks], qfr, S0); S1 = MFMA32(kf[1][ks], qfr, S1); }
;                 }
;                 __builtin_amdgcn_sched_barrier(0);
; #pragma unroll
;                 for (int i = 0; i < 2; ++i) gv[i] = *(const u32x4*)(vg + (size_t)i * 64 * M_TOK + key0 + 64);
;                 bf16x8 vf[4][2];
; #pragma unroll
;                 for (int d = 0; d < 4; ++d)
; #pragma unroll
;                     for (int s2 = 0; s2 < 2; ++s2) vf[d][s2] = *(const LAS bf16x8*)(buf + voff + d * 32 * DA_VP + (16 * s2) * 2);
;                 const float base = slope2 * (float)(key0 + 8 * hh - qpos), b32 = 32.f * slope2;
; #pragma unroll
;                 for (int i = 0; i < 16; ++i) { S0[i] = S0[i] * c1 + cb[i]; S1[i] = S1[i] * c1 + cb[i]; }
;                 float mx = -INFINITY, mx1 = -INFINITY;
; #pragma unroll
;                 for (int i = 0; i < 16; ++i) { mx = fmaxf(mx, S0[i]); mx1 = fmaxf(mx1, S1[i]); }
;                 mx = fmaxf(mx, mx1 + b32) + base;
;                 mx = fmaxf(mx, __shfl_xor(mx, 32));
.LBB0_424:
	s_cmp_lt_u32 s68, 4
	s_cbranch_scc0 .Lstg_g1_top
.Lstg_h1:
	s_add_i32 s14, s16, 64
	s_ashr_i32 s15, s14, 31
	s_lshl_b64 s[26:27], s[14:15], 12
	v_lshl_add_u64 v[66:67], v[114:115], 0, s[26:27]
	s_add_i32 s26, s16, 0x60
	s_ashr_i32 s27, s26, 31
	s_lshl_b64 s[26:27], s[26:27], 12
	global_load_dwordx4 v[98:101], v[66:67], off offset:2048
	v_lshl_add_u64 v[66:67], v[114:115], 0, s[26:27]
	global_load_dwordx4 v[102:105], v[66:67], off offset:2048
	s_bitcmp1_b32 s25, 0
	s_cselect_b32 s2, 0x8c00, 0
	s_add_i32 s2, s2, 0
	v_add_u32_e32 v70, s2, v153
	ds_read_b128 v[126:129], v217
	ds_read_b128 v[66:69], v70
	ds_read_b128 v[130:133], v217 offset:1024
	ds_read_b128 v[82:85], v70 offset:32
	ds_read_b128 v[134:137], v217 offset:2048
	ds_read_b128 v[86:89], v70 offset:64
	ds_read_b128 v[138:141], v217 offset:3072
	ds_read_b128 v[90:93], v70 offset:96
	ds_read_b128 v[94:97], v70 offset:8704
	ds_read_b128 v[106:109], v70 offset:8736
	ds_read_b128 v[110:113], v70 offset:8768
	ds_read_b128 v[122:125], v70 offset:8800
	v_mov_b32_e32 v121, v159
	v_mov_b32_e32 v0, v218
	s_waitcnt lgkmcnt(10)
	v_mfma_f32_32x32x16_bf16 v[66:81], v[66:69], v[126:129], 0
	s_ashr_i32 s17, s16, 31
	s_mov_b32 s3, 0x400000
	v_add_u32_e32 v118, s16, v120
	v_add_u32_e32 v191, s2, v211
	s_waitcnt lgkmcnt(8)
	v_mfma_f32_32x32x16_bf16 v[66:81], v[82:85], v[130:133], v[66:81]
	s_waitcnt lgkmcnt(6)
	v_mfma_f32_32x32x16_bf16 v[66:81], v[86:89], v[134:137], v[66:81]
	s_waitcnt lgkmcnt(4)
	v_mfma_f32_32x32x16_bf16 v[66:81], v[90:93], v[138:141], v[66:81]
	s_waitcnt lgkmcnt(3)
	v_mfma_f32_32x32x16_bf16 v[82:97], v[94:97], v[126:129], 0
	s_nop 10
	v_fmamk_f32 v127, v66, 0x3e38aa3b, v192
	v_max_f32_e32 v66, 0xff800000, v127
	v_fmamk_f32 v129, v69, 0x3e38aa3b, v189
	v_fmamk_f32 v159, v74, 0x3e38aa3b, v182
	v_fmamk_f32 v193, v75, 0x3e38aa3b, v183
	v_fmamk_f32 v196, v76, 0x3e38aa3b, v180
	v_cvt_f32_i32_e32 v126, v118
	s_waitcnt lgkmcnt(2)
	v_mfma_f32_32x32x16_bf16 v[82:97], v[106:109], v[130:133], v[82:97]
	v_lshl_add_u64 v[106:107], s[16:17], 1, v[116:117]
	v_add_co_u32_e32 v108, vcc, s3, v106
	v_fmamk_f32 v131, v70, 0x3e38aa3b, v186
	s_nop 0
	v_addc_co_u32_e32 v109, vcc, 0, v107, vcc
	v_fmamk_f32 v133, v71, 0x3e38aa3b, v187
	s_waitcnt lgkmcnt(1)
	v_mfma_f32_32x32x16_bf16 v[82:97], v[110:113], v[134:137], v[82:97]
	global_load_dwordx4 v[110:113], v[106:107], off offset:128
	s_nop 0
	global_load_dwordx4 v[106:109], v[108:109], off offset:128
	v_fmamk_f32 v135, v72, 0x3e38aa3b, v184
	v_fmamk_f32 v137, v73, 0x3e38aa3b, v185
	v_fmamk_f32 v199, v77, 0x3e38aa3b, v181
	v_fmamk_f32 v200, v78, 0x3e38aa3b, v178
	v_fmamk_f32 v204, v79, 0x3e38aa3b, v179
	v_fmamk_f32 v207, v80, 0x3e38aa3b, v176
	s_waitcnt lgkmcnt(0)
	v_mfma_f32_32x32x16_bf16 v[82:97], v[122:125], v[138:141], v[82:97]
	s_cmp_lt_u32 s68, 4
	s_cbranch_scc0 .Lstg_nomid
	s_barrier
.Lstg_nomid:
	v_fmamk_f32 v123, v67, 0x3e38aa3b, v160
	v_fmamk_f32 v125, v68, 0x3e38aa3b, v188
	v_max3_f32 v66, v66, v123, v125
	v_max3_f32 v66, v66, v129, v131
	v_max3_f32 v66, v66, v133, v135
	v_max3_f32 v66, v66, v137, v159
	v_max3_f32 v66, v66, v193, v196
	s_nop 4
	v_fmamk_f32 v122, v82, 0x3e38aa3b, v192
	v_fmamk_f32 v124, v83, 0x3e38aa3b, v160
	v_fmamk_f32 v128, v84, 0x3e38aa3b, v188
	v_fmamk_f32 v130, v85, 0x3e38aa3b, v189
	v_max3_f32 v67, v122, s54, v124
	v_fmamk_f32 v132, v86, 0x3e38aa3b, v186
	v_fmamk_f32 v134, v87, 0x3e38aa3b, v187
	v_max3_f32 v67, v67, v128, v130
	v_fmamk_f32 v136, v88, 0x3e38aa3b, v184
	v_fmamk_f32 v143, v89, 0x3e38aa3b, v185
	v_max3_f32 v67, v67, v132, v134
	v_fmamk_f32 v169, v90, 0x3e38aa3b, v182
	v_fmamk_f32 v195, v91, 0x3e38aa3b, v183
	v_max3_f32 v67, v67, v136, v143
	v_fmamk_f32 v198, v92, 0x3e38aa3b, v180
	v_fmamk_f32 v202, v93, 0x3e38aa3b, v181
	v_max3_f32 v67, v67, v169, v195
	v_fmamk_f32 v203, v94, 0x3e38aa3b, v178
	v_fmamk_f32 v206, v95, 0x3e38aa3b, v179
	v_max3_f32 v67, v67, v198, v202
	v_fmamk_f32 v219, v96, 0x3e38aa3b, v176
	v_fmamk_f32 v222, v97, 0x3e38aa3b, v177
	v_max3_f32 v67, v67, v203, v206
	v_max3_f32 v66, v66, v199, v200
	v_max3_f32 v67, v67, v219, v222
	v_fmamk_f32 v220, v81, 0x3e38aa3b, v177
	v_max3_f32 v66, v66, v204, v207
	v_add_f32_e32 v67, v157, v67
	v_max3_f32 v66, v66, v220, v67
	v_fmac_f32_e32 v66, v160, v126
	v_mov_b32_e32 v67, v66
	s_nop 1
	v_permlane32_swap_b32_e32 v66, v67
	ds_read_b128 v[94:97], v191 offset:17408
	ds_read_b128 v[90:93], v191 offset:17440
	ds_read_b128 v[86:89], v191 offset:22016
	ds_read_b128 v[82:85], v191 offset:22048
	s_waitcnt lgkmcnt(4)
; DI float fexp2(float x) { return __builtin_amdgcn_exp2f(x); }
; DI void diff_attn_phase(int wv, LAS unsigned char* lds, const bf16_t* qk, const bf16_t* vt, bf16_t* ob, const float* lq1, const float* lk1, const float* lq2, const float* lk2,
;                         const float* subg, int layer_idx) {
;     ...
;                 {
;                     const float mn = fmaxf(m, mx), alpha = fexp2(m - mn); m = mn; l *= alpha;
; #pragma unroll
;                     for (int d = 0; d < 4; ++d) O[d] = O[d] * alpha;
;                 }
;                 const float off = base - m, off1 = off + b32;
;                 float ps = 0.f;
; #pragma unroll
;                 for (int i = 0; i < 16; ++i) { S0[i] = fexp2(S0[i] + off); S1[i] = fexp2(S1[i] + off1); ps += S0[i] + S1[i]; }
;                 l += ps;
;                 const bf16x8 p0 = pack8(S0, 0), p1 = pack8(S0, 1), p2 = pack8(S1, 0), p3 = pack8(S1, 1);
	v_max3_f32 v218, v0, v66, v67
	v_sub_f32_e32 v0, v0, v218
	v_fma_f32 v126, v160, v126, -v218
	v_exp_f32_e32 v118, v0
	v_add_f32_e32 v223, v157, v126
	v_add_f32_e32 v0, v127, v126
	v_exp_f32_e32 v127, v0
	v_add_f32_e32 v0, v122, v223
	v_add_f32_e32 v122, v125, v126
	v_exp_f32_e32 v224, v0
	v_add_f32_e32 v0, v123, v126
	v_exp_f32_e32 v123, v122
	v_add_f32_e32 v122, v128, v223
	v_exp_f32_e32 v225, v122
	v_add_f32_e32 v122, v129, v126
	v_exp_f32_e32 v140, v122
	v_add_f32_e32 v122, v130, v223
	v_exp_f32_e32 v142, v122
	v_add_f32_e32 v122, v133, v126
	v_exp_f32_e32 v144, v122
	v_add_f32_e32 v122, v134, v223
	v_exp_f32_e32 v168, v122
	v_add_f32_e32 v122, v137, v126
	v_exp_f32_e32 v170, v122
	v_add_f32_e32 v122, v143, v223
	v_add_f32_e32 v129, v169, v223
	v_exp_f32_e32 v194, v122
	v_add_f32_e32 v122, v193, v126
	v_exp_f32_e32 v134, v129
	v_add_f32_e32 v129, v196, v126
	v_exp_f32_e32 v196, v122
	v_add_f32_e32 v122, v195, v223
	v_add_f32_e32 v125, v132, v223
	v_add_f32_e32 v130, v198, v223
	v_exp_f32_e32 v198, v122
	v_add_f32_e32 v122, v199, v126
	v_exp_f32_e32 v132, v125
	v_add_f32_e32 v125, v135, v126
	v_exp_f32_e32 v135, v130
	v_add_f32_e32 v130, v200, v126
	v_exp_f32_e32 v200, v122
	v_add_f32_e32 v122, v202, v223
	v_exp_f32_e32 v202, v122
	v_add_f32_e32 v122, v204, v126
	ds_read_b128 v[78:81], v191 offset:26624
	ds_read_b128 v[74:77], v191 offset:26656
	ds_read_b128 v[70:73], v191 offset:31232
	ds_read_b128 v[66:69], v191 offset:31264
	v_exp_f32_e32 v204, v122
	v_add_f32_e32 v122, v206, v223
	v_exp_f32_e32 v138, v0
	v_add_f32_e32 v0, v124, v223
	v_add_f32_e32 v124, v131, v126
	v_add_f32_e32 v128, v136, v223
	v_add_f32_e32 v131, v203, v223
	v_exp_f32_e32 v206, v122
	v_add_f32_e32 v122, v220, v126
	v_exp_f32_e32 v133, v128
	v_add_f32_e32 v128, v159, v126
	v_exp_f32_e32 v136, v131
	v_add_f32_e32 v131, v207, v126
	v_add_f32_e32 v137, v219, v223
	v_exp_f32_e32 v220, v122
	v_add_f32_e32 v122, v222, v223
	v_exp_f32_e32 v0, v0
	v_exp_f32_e32 v124, v124
	v_exp_f32_e32 v125, v125
	v_exp_f32_e32 v128, v128
	v_exp_f32_e32 v129, v129
	v_exp_f32_e32 v130, v130
	v_exp_f32_e32 v131, v131
	v_exp_f32_e32 v137, v137
	v_exp_f32_e32 v222, v122
	v_pk_mul_f32 v[64:65], v[64:65], v[118:119] op_sel_hi:[1,0]
	v_pk_mul_f32 v[62:63], v[62:63], v[118:119] op_sel_hi:[1,0]
	v_pk_mul_f32 v[60:61], v[60:61], v[118:119] op_sel_hi:[1,0]
	v_pk_mul_f32 v[58:59], v[58:59], v[118:119] op_sel_hi:[1,0]
	v_pk_mul_f32 v[56:57], v[56:57], v[118:119] op_sel_hi:[1,0]
	v_pk_mul_f32 v[54:55], v[54:55], v[118:119] op_sel_hi:[1,0]
	v_pk_mul_f32 v[52:53], v[52:53], v[118:119] op_sel_hi:[1,0]
	v_pk_mul_f32 v[50:51], v[50:51], v[118:119] op_sel_hi:[1,0]
	v_pk_mul_f32 v[48:49], v[48:49], v[118:119] op_sel_hi:[1,0]
	v_pk_mul_f32 v[46:47], v[46:47], v[118:119] op_sel_hi:[1,0]
	v_pk_mul_f32 v[44:45], v[44:45], v[118:119] op_sel_hi:[1,0]
	v_pk_mul_f32 v[42:43], v[42:43], v[118:119] op_sel_hi:[1,0]
	v_pk_mul_f32 v[40:41], v[40:41], v[118:119] op_sel_hi:[1,0]
	v_pk_mul_f32 v[38:39], v[38:39], v[118:119] op_sel_hi:[1,0]
	v_pk_mul_f32 v[36:37], v[36:37], v[118:119] op_sel_hi:[1,0]
	v_pk_mul_f32 v[34:35], v[34:35], v[118:119] op_sel_hi:[1,0]
	v_pk_mul_f32 v[32:33], v[32:33], v[118:119] op_sel_hi:[1,0]
	v_pk_mul_f32 v[30:31], v[30:31], v[118:119] op_sel_hi:[1,0]
	v_pk_mul_f32 v[28:29], v[28:29], v[118:119] op_sel_hi:[1,0]
	v_pk_mul_f32 v[26:27], v[26:27], v[118:119] op_sel_hi:[1,0]
	v_pk_mul_f32 v[24:25], v[24:25], v[118:119] op_sel_hi:[1,0]
	v_pk_mul_f32 v[22:23], v[22:23], v[118:119] op_sel_hi:[1,0]
	v_pk_mul_f32 v[20:21], v[20:21], v[118:119] op_sel_hi:[1,0]
	v_pk_mul_f32 v[18:19], v[18:19], v[118:119] op_sel_hi:[1,0]
	v_pk_mul_f32 v[16:17], v[16:17], v[118:119] op_sel_hi:[1,0]
	v_pk_mul_f32 v[14:15], v[14:15], v[118:119] op_sel_hi:[1,0]
	v_pk_mul_f32 v[12:13], v[12:13], v[118:119] op_sel_hi:[1,0]
	v_pk_mul_f32 v[10:11], v[10:11], v[118:119] op_sel_hi:[1,0]
	v_pk_mul_f32 v[8:9], v[8:9], v[118:119] op_sel_hi:[1,0]
	v_pk_mul_f32 v[6:7], v[6:7], v[118:119] op_sel_hi:[1,0]
	v_pk_mul_f32 v[4:5], v[4:5], v[118:119] op_sel_hi:[1,0]
	v_pk_mul_f32 v[2:3], v[2:3], v[118:119] op_sel_hi:[1,0]
	v_add_f32_e32 v139, v127, v224
	v_add_f32_e32 v141, v123, v225
	v_add_f32_e32 v145, v124, v132
	v_add_f32_e32 v171, v125, v133
	v_add_f32_e32 v197, v128, v134
	v_add_f32_e32 v201, v129, v135
	v_add_f32_e32 v205, v130, v136
	v_add_f32_e32 v221, v131, v137
	v_cvt_pk_bf16_f32 v122, v127, v138
	v_cvt_pk_bf16_f32 v123, v123, v140
	v_cvt_pk_bf16_f32 v124, v124, v144
	v_cvt_pk_bf16_f32 v125, v125, v170
	v_cvt_pk_bf16_f32 v126, v128, v196
	v_cvt_pk_bf16_f32 v127, v129, v200
	v_cvt_pk_bf16_f32 v128, v130, v204
	v_cvt_pk_bf16_f32 v129, v131, v220
	v_cvt_pk_bf16_f32 v130, v224, v0
	v_cvt_pk_bf16_f32 v131, v225, v142
	v_cvt_pk_bf16_f32 v132, v132, v168
	v_cvt_pk_bf16_f32 v133, v133, v194
	v_cvt_pk_bf16_f32 v134, v134, v198
	v_cvt_pk_bf16_f32 v135, v135, v202
	v_cvt_pk_bf16_f32 v136, v136, v206
	v_cvt_pk_bf16_f32 v137, v137, v222
	s_cmp_lt_u32 s68, 4
	s_cbranch_scc0 .Lstg_wblk
; #define LAS __attribute__((address_space(3)))
; #define MFMA32(a, b, c) __builtin_amdgcn_mfma_f32_32x32x16_bf16((a), (b), (c), 0, 0, 0)
; DI void diff_attn_phase(int wv, LAS unsigned char* lds, const bf16_t* qk, const bf16_t* vt, bf16_t* ob, const float* lq1, const float* lk1, const float* lq2, const float* lk2,
;                         const float* subg, int layer_idx) {
;     ...
;                 for (int d = 0; d < 4; ++d) { O[d] = MFMA32(vf[d][0], p0, O[d]); O[d] = MFMA32(vf[d][1], p1, O[d]); }
;                 __builtin_amdgcn_sched_barrier(0);
; #pragma unroll
;                 for (int d = 0; d < 4; ++d)
; #pragma unroll
;                     for (int s2 = 0; s2 < 2; ++s2) vf[d][s2] = *(const LAS bf16x8*)(buf + voff + d * 32 * DA_VP + (32 + 16 * s2) * 2);
; #pragma unroll
;                 for (int d = 0; d < 4; ++d) { O[d] = MFMA32(vf[d][0], p2, O[d]); O[d] = MFMA32(vf[d][1], p3, O[d]); }
;             }
;             if (more) {
;                 LAS unsigned char* nb = lds + ((t + 1) & 1) * DA_BUF;
; #pragma unroll
;                 for (int i = 0; i < 2; ++i) { *(LAS u32x4*)(nb + kst_off + i * 32 * DA_KP) = gk[i]; *(LAS u32x4*)(nb + vst_off + i * 64 * DA_VP) = gv[i]; } }
;             __syncthreads();
;         }
.Lstg_pv:
	s_waitcnt lgkmcnt(5)
	v_mfma_f32_32x32x16_bf16 v[34:49], v[86:89], v[122:125], v[34:49]
	s_waitcnt lgkmcnt(4)
	v_mfma_f32_32x32x16_bf16 v[34:49], v[82:85], v[126:129], v[34:49]
	v_add_f32_e64 v82, v138, v0
	v_add_f32_e64 v83, v139, v1
	s_waitcnt lgkmcnt(3)
	v_mfma_f32_32x32x16_bf16 v[18:33], v[78:81], v[122:125], v[18:33]
	v_add_f32_e64 v78, v82, v82
	v_add_f32_e64 v79, v82, v83
	v_mov_b32_e32 v143, v79
	v_add_f32_e64 v78, v140, v142
	v_add_f32_e64 v79, v141, v143
	v_pk_add_f32 v[78:79], v[78:79], v[78:79] op_sel_hi:[0,1]
	v_mov_b32_e32 v169, v79
	v_pk_add_f32 v[78:79], v[144:145], v[168:169]
	v_mfma_f32_32x32x16_bf16 v[50:65], v[94:97], v[122:125], v[50:65]
	v_pk_add_f32 v[78:79], v[78:79], v[78:79] op_sel_hi:[0,1]
	v_mov_b32_e32 v195, v79
	s_waitcnt lgkmcnt(1)
	v_mfma_f32_32x32x16_bf16 v[2:17], v[70:73], v[122:125], v[2:17]
	v_mfma_f32_32x32x16_bf16 v[18:33], v[74:77], v[126:129], v[18:33]
	v_add_f32_e64 v74, v170, v194
	v_add_f32_e64 v75, v171, v195
	v_pk_add_f32 v[74:75], v[74:75], v[74:75] op_sel_hi:[0,1]
	v_mov_b32_e32 v199, v75
	v_pk_add_f32 v[74:75], v[196:197], v[198:199]
	s_nop 0
	v_pk_add_f32 v[74:75], v[74:75], v[74:75] op_sel_hi:[0,1]
	v_mov_b32_e32 v203, v75
	v_mfma_f32_32x32x16_bf16 v[50:65], v[90:93], v[126:129], v[50:65]
	v_add_f32_e64 v70, v200, v202
	v_add_f32_e64 v71, v201, v203
	v_pk_add_f32 v[70:71], v[70:71], v[70:71] op_sel_hi:[0,1]
	v_mov_b32_e32 v207, v71
	v_pk_add_f32 v[70:71], v[204:205], v[206:207]
	s_nop 0
	v_pk_add_f32 v[70:71], v[70:71], v[70:71] op_sel_hi:[0,1]
	s_waitcnt lgkmcnt(0)
	v_mfma_f32_32x32x16_bf16 v[2:17], v[66:69], v[126:129], v[2:17]
	v_mov_b32_e32 v223, v71
	v_add_f32_e64 v70, v220, v222
	v_add_f32_e64 v71, v221, v223
	v_add_f32_e32 v159, v70, v71
	ds_read_b128 v[66:69], v191 offset:17472
	ds_read_b128 v[70:73], v191 offset:17504
	ds_read_b128 v[78:81], v191 offset:22080
	ds_read_b128 v[82:85], v191 offset:22112
	ds_read_b128 v[86:89], v191 offset:26688
	ds_read_b128 v[90:93], v191 offset:26720
	ds_read_b128 v[94:97], v191 offset:31296
	ds_read_b128 v[74:77], v191 offset:31328
	v_fmac_f32_e32 v159, v121, v118
	s_waitcnt lgkmcnt(7)
	v_mfma_f32_32x32x16_bf16 v[50:65], v[66:69], v[130:133], v[50:65]
	s_waitcnt lgkmcnt(6)
	v_mfma_f32_32x32x16_bf16 v[50:65], v[70:73], v[134:137], v[50:65]
	s_waitcnt lgkmcnt(5)
	v_mfma_f32_32x32x16_bf16 v[34:49], v[78:81], v[130:133], v[34:49]
	s_waitcnt lgkmcnt(4)
	v_mfma_f32_32x32x16_bf16 v[34:49], v[82:85], v[134:137], v[34:49]
	s_waitcnt lgkmcnt(3)
	v_mfma_f32_32x32x16_bf16 v[18:33], v[86:89], v[130:133], v[18:33]
	s_waitcnt lgkmcnt(2)
	v_mfma_f32_32x32x16_bf16 v[18:33], v[90:93], v[134:137], v[18:33]
	s_waitcnt lgkmcnt(1)
	v_mfma_f32_32x32x16_bf16 v[2:17], v[94:97], v[130:133], v[2:17]
	s_waitcnt lgkmcnt(0)
	v_mfma_f32_32x32x16_bf16 v[2:17], v[74:77], v[134:137], v[2:17]
	s_cmp_lt_u32 s68, 4
	s_cbranch_scc0 .Lstg_g1_after_pv
.Lstg_wblk:
	s_add_i32 s25, s25, 1
	s_bitcmp1_b32 s25, 0
	s_cselect_b32 s2, 0x8c00, 0
	s_add_i32 s2, s2, 0
	v_add_u32_e32 v226, s2, v167
	v_add_u32_e32 v227, s2, v208
	s_mov_b32 s16, s14
	s_waitcnt vmcnt(3)
	ds_write_b128 v226, v[98:101]
	s_waitcnt vmcnt(1)
	ds_write_b128 v227, v[110:113] offset:17408
	ds_write_b128 v226, v[102:105] offset:8704
	s_waitcnt vmcnt(0)
	ds_write_b128 v227, v[106:109] offset:26624
	s_waitcnt lgkmcnt(0)
	s_barrier
	s_cmp_eq_u32 s1, s25
	s_cbranch_scc0 .LBB0_424
	s_cmp_lt_u32 s68, 4
	s_cbranch_scc1 .Lstg_exit
	s_mov_b32 s26, 1
	s_branch .Lstg_pv
.Lstg_g1_top:
	s_cmp_eq_u32 s25, 0
	s_cbranch_scc1 .Lstg_g1_mid
	s_mov_b32 s26, 0
	s_branch .Lstg_pv
.Lstg_g1_after_pv:
	s_cmp_eq_u32 s26, 1
	s_cbranch_scc1 .Lstg_g1_drained
.Lstg_g1_mid:
	s_waitcnt lgkmcnt(0)
	s_barrier
	s_branch .Lstg_h1

; #define LAS __attribute__((address_space(3)))
; DI void diff_attn_phase(int wv, LAS unsigned char* lds, const bf16_t* qk, const bf16_t* vt, bf16_t* ob, const float* lq1, const float* lk1, const float* lq2, const float* lk2,
;                         const float* subg, int layer_idx) {
;     ...
;             if (more) {
;                 LAS unsigned char* nb = lds + ((t + 1) & 1) * DA_BUF;
; #pragma unroll
;                 for (int i = 0; i < 2; ++i) { *(LAS u32x4*)(nb + kst_off + i * 32 * DA_KP) = gk[i]; *(LAS u32x4*)(nb + vst_off + i * 64 * DA_VP) = gv[i]; } }
;             __syncthreads();
;         }
.Lstg_exit:
	s_barrier
	s_branch .LBB0_427
